# helper-WG f32->bf16 conversion loop: 4x unrolled with four loads in flight when the grid stride is a power of two
# speedup vs baseline: 1.0137x; 1.0049x over previous
; __device__ __forceinline__ unsigned cvt_pk_bf16(float lo, float hi) { unsigned r; asm volatile("v_cvt_pk_bf16_f32 %0, %1, %2" : "=v"(r) : "v"(lo), "v"(hi)); return r; }
; __global__ void __launch_bounds__(512, 2) mega(Params P0) {
;     ...
;                     const int nun = (HALF_TOK / 256) * (2 * DFF / 256), rem = nun % G; const int nfree = rem ? G - rem : 0, sub = rem ? bid - rem : -1;
;                     if (sub >= 0) { asm volatile("s_waitcnt vmcnt(0)" ::: "memory"); __syncthreads();
;                         pg8::Gemm g2{(const bf16_t*)(ws + WS_PBF), (const bf16_t*)(ws + WS_WPP), NTOK, DM, PLE}; pg8::StaticOrder S2; S2.init(NTOK, DM, nfree, sub); S2.hi = 256;
;                         EpiPP E2{(bf16_t*)(ws + WS_PPT), (bf16_t*)dob}; pg8::gemm_phase(lds, g2, S2, E2); } }
;                 if (half == 0) {
;                     const int nun = (HALF_TOK / 256) * (2 * DFF / 256), rem = nun % G; const int nfree = rem ? G - rem : G, sub = rem ? bid - rem : bid;
;                     if (sub >= 0) { bf16_t* pbf = (bf16_t*)(ws + WS_PBF); int tid = threadIdx.x; asm volatile("" : "+v"(tid));
;                         for (int i = sub * 512 + tid; i < NTOK * PLE / 4; i += nfree * 512) { const int row = i >> 6, c4 = i & 63; const f32x4 v = *(const f32x4*)(prow(P, row) + 4 * c4);
;                             u32x2 w; w.x = cvt_pk_bf16(v[0], v[1]); w.y = cvt_pk_bf16(v[2], v[3]); *(u32x2*)(pbf + (size_t)row * PLE + 4 * c4) = w; }
.LBB0_978:
	s_cmp_gt_u32 s84, 1
	v_readlane_b32 s26, v255, 24
	s_cbranch_scc1 .LBB0_1022
	v_readlane_b32 s0, v255, 18
	s_abs_i32 s0, s0
	s_sub_i32 s2, 0, s0
	v_cvt_f32_u32_e32 v0, s0
	v_readlane_b32 s26, v255, 24
	v_rcp_iflag_f32_e32 v0, v0
	s_nop 0
	v_mul_f32_e32 v0, 0x4f7ffffe, v0
	v_cvt_u32_f32_e32 v0, v0
	s_nop 0
	v_readfirstlane_b32 s3, v0
	s_mul_i32 s2, s2, s3
	s_mul_hi_u32 s2, s3, s2
	s_add_i32 s3, s3, s2
	s_mul_hi_u32 s2, s3, 0x580
	s_mul_i32 s2, s2, s0
	s_sub_i32 s2, 0x580, s2
	s_sub_i32 s3, s2, s0
	s_cmp_ge_u32 s2, s0
	s_cselect_b32 s2, s3, s2
	s_sub_i32 s3, s2, s0
	s_cmp_ge_u32 s2, s0
	s_cselect_b32 s15, s3, s2
	s_sub_i32 s0, s77, s15
	s_cmp_lt_i32 s0, 0
	s_cbranch_scc1 .LBB0_1022
	v_mov_b32_e32 v0, v162
	v_readlane_b32 s6, v255, 18
	s_mov_b32 s2, 0x200000
	v_lshl_add_u32 v2, s0, 9, v0
	s_sub_i32 s8, s6, s15
	v_cmp_gt_i32_e32 vcc, s2, v2
	s_and_saveexec_b64 s[2:3], vcc
	v_readlane_b32 s40, v254, 34
	s_movk_i32 s12, 0x4000
	v_readlane_b32 s44, v254, 38
	v_readlane_b32 s45, v254, 39
	v_readlane_b32 s46, v254, 40
	v_readlane_b32 s47, v254, 41
	v_readlane_b32 s41, v254, 35
	v_readlane_b32 s42, v254, 36
	v_readlane_b32 s43, v254, 37
	v_readlane_b32 s48, v254, 42
	v_readlane_b32 s49, v254, 43
	v_readlane_b32 s50, v254, 44
	v_readlane_b32 s51, v254, 45
	v_readlane_b32 s52, v254, 46
	v_readlane_b32 s53, v254, 47
	v_readlane_b32 s54, v254, 48
	v_readlane_b32 s55, v254, 49
	s_cbranch_execz .LBB0_983
	s_add_u32 s4, s22, 0xc000000
	s_addc_u32 s5, s23, 0
	s_lshl_b32 s6, s6, 11
	s_lshl_b32 s7, s15, 11
	s_lshl_b32 s9, s8, 9
	s_waitcnt lgkmcnt(0)
	v_lshlrev_b32_e32 v3, 2, v2
	s_sub_i32 s10, s6, s7
	s_mov_b64 s[6:7], 0
	s_add_i32 s11, s9, -1
	s_and_b32 s11, s11, s9
	s_cmp_lg_u32 s11, 0
	s_cbranch_scc1 .LBB0_982
	s_cmp_gt_u32 s9, 0x80000
	s_cbranch_scc1 .LBB0_982
	s_ff1_i32_b32 s11, s9
	s_lshr_b32 s11, 0x80000, s11
	v_and_b32_e32 v11, 63, v2
	v_ashrrev_i32_e32 v12, 6, v2
	v_lshlrev_b32_e32 v14, 4, v11
	v_mov_b32_e32 v15, 0
	v_lshlrev_b32_e32 v18, 3, v11
	v_mov_b32_e32 v19, 0
	v_mov_b32_e32 v28, 0xff000000
	v_mov_b32_e32 v29, -1
	v_lshl_add_u64 v[16:17], s[46:47], 0, v[14:15]
	v_lshl_add_u64 v[14:15], s[44:45], 0, v[14:15]
	v_lshl_add_u64 v[18:19], s[4:5], 0, v[18:19]
	v_lshl_add_u64 v[16:17], v[16:17], 0, v[28:29]
	v_mov_b32_e32 v20, 0x400
	v_mov_b32_e32 v21, 0x200
	v_mov_b32_e32 v23, s9
	v_lshrrev_b32_e32 v23, 6, v23
	v_lshlrev_b32_e32 v22, 2, v23
	v_add_u32_e32 v24, v12, v23
	v_add_u32_e32 v25, v24, v23
	v_add_u32_e32 v26, v25, v23
.Lcvtx_loop:
	v_cmp_gt_i32_e32 vcc, 0x4000, v12
	s_nop 1
	v_cndmask_b32_e32 v4, v16, v14, vcc
	v_cndmask_b32_e32 v5, v17, v15, vcc
	s_nop 0
	v_mad_u64_u32 v[4:5], vcc, v12, v20, v[4:5]
	s_nop 0
	global_load_dwordx4 v[32:35], v[4:5], off
	v_cmp_gt_i32_e32 vcc, 0x4000, v24
	s_nop 1
	v_cndmask_b32_e32 v6, v16, v14, vcc
	v_cndmask_b32_e32 v7, v17, v15, vcc
	s_nop 0
	v_mad_u64_u32 v[6:7], vcc, v24, v20, v[6:7]
	s_nop 0
	global_load_dwordx4 v[36:39], v[6:7], off
	v_cmp_gt_i32_e32 vcc, 0x4000, v25
	s_nop 1
	v_cndmask_b32_e32 v8, v16, v14, vcc
	v_cndmask_b32_e32 v9, v17, v15, vcc
	s_nop 0
	v_mad_u64_u32 v[8:9], vcc, v25, v20, v[8:9]
	s_nop 0
	global_load_dwordx4 v[40:43], v[8:9], off
	v_cmp_gt_i32_e32 vcc, 0x4000, v26
	s_nop 1
	v_cndmask_b32_e32 v30, v16, v14, vcc
	v_cndmask_b32_e32 v31, v17, v15, vcc
	s_nop 0
	v_mad_u64_u32 v[30:31], vcc, v26, v20, v[30:31]
	s_nop 0
	global_load_dwordx4 v[44:47], v[30:31], off
	v_mad_u64_u32 v[4:5], vcc, v12, v21, v[18:19]
	v_add_u32_e32 v12, v12, v22
	s_waitcnt vmcnt(3)
	v_cvt_pk_bf16_f32 v32, v32, v33
	v_cvt_pk_bf16_f32 v33, v34, v35
	s_nop 1
	global_store_dwordx2 v[4:5], v[32:33], off
	v_mad_u64_u32 v[6:7], vcc, v24, v21, v[18:19]
	v_add_u32_e32 v24, v24, v22
	s_waitcnt vmcnt(3)
	v_cvt_pk_bf16_f32 v36, v36, v37
	v_cvt_pk_bf16_f32 v37, v38, v39
	s_nop 1
	global_store_dwordx2 v[6:7], v[36:37], off
	v_mad_u64_u32 v[8:9], vcc, v25, v21, v[18:19]
	v_add_u32_e32 v25, v25, v22
	s_waitcnt vmcnt(3)
	v_cvt_pk_bf16_f32 v40, v40, v41
	v_cvt_pk_bf16_f32 v41, v42, v43
	s_nop 1
	global_store_dwordx2 v[8:9], v[40:41], off
	v_mad_u64_u32 v[30:31], vcc, v26, v21, v[18:19]
	v_add_u32_e32 v26, v26, v22
	s_waitcnt vmcnt(3)
	v_cvt_pk_bf16_f32 v44, v44, v45
	v_cvt_pk_bf16_f32 v45, v46, v47
	s_nop 1
	global_store_dwordx2 v[30:31], v[44:45], off
	s_sub_i32 s11, s11, 1
	s_cmp_lg_u32 s11, 0
	s_cbranch_scc1 .Lcvtx_loop
	s_branch .LBB0_983
